# dense attention loop: first P.V block's transpose reads of each half-iteration issued in the tail of the preceding QK^T (LDS latency hidden at the phase transition)
# baseline (speedup 1.0000x reference)
; __device__ __forceinline__ void finishSM(f32x16& p0, f32x16& p1, float alpha, float& l_reg, bf16x8& pa0, bf16x8& pa1, bf16x8& pa2, bf16x8& pa3) {
;   for (int r = 0; r < 16; ++r) p1[r] = __builtin_amdgcn_exp2f(p1[r]);
;   float ps = 0; for (int r = 0; r < 16; ++r) ps += p0[r]; for (int r = 0; r < 16; ++r) ps += p1[r];
;   { auto rr = __builtin_amdgcn_permlane32_swap(__float_as_uint(ps), __float_as_uint(ps), false, false);
;     ps = __uint_as_float(rr[0]) + __uint_as_float(rr[1]); }
;   l_reg = l_reg * alpha + ps;
;     ...
;   PK4(p0, 0, pa0); PK4(p0, 8, pa1); PK4(p1, 0, pa2); PK4(p1, 8, pa3);
;     ...
; }
; __device__ __forceinline__ void qkt(f32x16& p0, f32x16& p1, const bf16* Ks, const bf16x8* qr, int r32, int hi) {
;   p0 = f32x16{}; p1 = f32x16{};
;   for (int d0 = 0; d0 < 8; ++d0) { int cb = (d0 * 16 + hi * 8) * 2;
;     bf16x8 b0 = *reinterpret_cast<const bf16x8*>((const char*)Ks + KSWZ(r32, cb));
;     bf16x8 b1 = *reinterpret_cast<const bf16x8*>((const char*)Ks + KSWZ(32 + r32, cb));
;     p0 = __builtin_amdgcn_mfma_f32_32x32x16_bf16(b0, qr[d0], p0, 0, 0, 0);
;     p1 = __builtin_amdgcn_mfma_f32_32x32x16_bf16(b1, qr[d0], p1, 0, 0, 0); }
; }
; __device__ __forceinline__ int v_st(int k, int c) { const int kk = (k & ~0xC) | ((k & 4) << 1) | ((k & 8) >> 1); return ((kk >> 3) * 4 + (c >> 5)) * 512 + ((kk & 7) * 32 + (c & 31)) * 2; }
; __device__ __forceinline__ int v_rd_base(int lane) { return ((lane & 3) << 3) | (((lane >> 2) & 3) << 6) | (((lane >> 4) & 1) << 5) | (((lane >> 5) & 1) << 8); }
; template <int OFF> __device__ __forceinline__ s16x4 tr_read(int vb) {
;   s16x4 r; asm volatile("ds_read_b64_tr_b16 %0, %1 offset:%2" : "=&v"(r) : "v"(vb), "i"(OFF) : "memory"); return r;
; }
; template <int D0> __device__ __forceinline__ void pv_one(f32x16& od, int vb, bf16x8 pa0, bf16x8 pa1, bf16x8 pa2, bf16x8 pa3) {
;   const s16x4 l0 = tr_read<v_rd_off(D0, 0, 0)>(vb), h0 = tr_read<v_rd_off(D0, 0, 1)>(vb), l1 = tr_read<v_rd_off(D0, 1, 0)>(vb), h1 = tr_read<v_rd_off(D0, 1, 1)>(vb);
;   const s16x4 l2 = tr_read<v_rd_off(D0, 2, 0)>(vb), h2 = tr_read<v_rd_off(D0, 2, 1)>(vb), l3 = tr_read<v_rd_off(D0, 3, 0)>(vb), h3 = tr_read<v_rd_off(D0, 3, 1)>(vb);
;   asm volatile("s_waitcnt lgkmcnt(0)" ::: "memory"); SBAR();
;     ...
;   od = __builtin_amdgcn_mfma_f32_32x32x16_bf16(pa0, PK(l0, h0), od, 0, 0, 0);
;   od = __builtin_amdgcn_mfma_f32_32x32x16_bf16(pa1, PK(l1, h1), od, 0, 0, 0);
.LBB0_171:
	ds_read_b128 v[98:101], v218 offset:49152
	ds_read_b128 v[102:105], v218 offset:57344
	ds_read_b128 v[178:181], v223 offset:49152
	ds_read_b128 v[182:185], v223 offset:57344
	ds_read_b128 v[186:189], v227 offset:49152
	ds_read_b128 v[190:193], v227 offset:57344
	v_exp_f32_e32 v82, v82
	v_exp_f32_e32 v83, v83
	s_waitcnt lgkmcnt(5)
	v_mfma_f32_32x32x16_bf16 v[114:129], v[98:101], v[134:137], 0
	v_exp_f32_e32 v84, v84
	v_exp_f32_e32 v85, v85
	v_exp_f32_e32 v86, v86
	v_exp_f32_e32 v87, v87
	v_exp_f32_e32 v88, v88
	v_exp_f32_e32 v89, v89
	v_exp_f32_e32 v90, v90
	s_waitcnt lgkmcnt(4)
	v_mfma_f32_32x32x16_bf16 v[98:113], v[102:105], v[134:137], 0
	v_exp_f32_e32 v91, v91
	v_exp_f32_e32 v92, v92
	v_exp_f32_e32 v93, v93
	v_exp_f32_e32 v94, v94
	v_exp_f32_e32 v95, v95
	v_exp_f32_e32 v96, v96
	v_exp_f32_e32 v97, v97
	s_waitcnt lgkmcnt(2)
	v_mfma_f32_32x32x16_bf16 v[98:113], v[182:185], v[142:145], v[98:113]
	v_mfma_f32_32x32x16_bf16 v[114:129], v[178:181], v[142:145], v[114:129]
	ds_read_b128 v[178:181], v228 offset:49152
	ds_read_b128 v[194:197], v228 offset:57344
	ds_read_b128 v[198:201], v229 offset:49152
	ds_read_b128 v[202:205], v229 offset:57344
	ds_read_b128 v[206:209], v231 offset:49152
	ds_read_b128 v[238:241], v231 offset:57344
	ds_read_b128 v[242:245], v230 offset:49152
	ds_read_b128 v[246:249], v230 offset:57344
	ds_read_b128 v[182:185], v232 offset:49152
	ds_read_b128 v[250:253], v232 offset:57344
	s_waitcnt lgkmcnt(10)
	v_mfma_f32_32x32x16_bf16 v[98:113], v[190:193], v[130:133], v[98:113]
	v_mfma_f32_32x32x16_bf16 v[114:129], v[186:189], v[130:133], v[114:129]
	v_add_f32_e32 v186, 0, v66
	v_add_f32_e32 v186, v67, v186
	v_add_f32_e32 v186, v68, v186
	s_waitcnt lgkmcnt(8)
	v_mfma_f32_32x32x16_bf16 v[98:113], v[194:197], v[138:141], v[98:113]
	v_cvt_pk_bf16_f32 v194, v66, v67
	v_cvt_pk_bf16_f32 v195, v68, v69
	v_cvt_pk_bf16_f32 v196, v70, v71
	v_cvt_pk_bf16_f32 v197, v72, v73
	s_nop 0
	v_permlane32_swap_b32_e32 v194, v196
	v_mfma_f32_32x32x16_bf16 v[114:129], v[178:181], v[138:141], v[114:129]
	v_add_f32_e32 v178, v69, v186
	v_add_f32_e32 v178, v70, v178
	v_add_f32_e32 v178, v71, v178
	v_add_f32_e32 v178, v72, v178
	v_add_f32_e32 v178, v73, v178
	v_add_f32_e32 v178, v74, v178
	v_add_f32_e32 v178, v75, v178
	s_waitcnt lgkmcnt(6)
	v_mfma_f32_32x32x16_bf16 v[98:113], v[202:205], v[150:153], v[98:113]
	v_add_f32_e32 v178, v76, v178
	v_add_f32_e32 v178, v77, v178
	v_add_f32_e32 v178, v78, v178
	v_add_f32_e32 v178, v79, v178
	v_add_f32_e32 v178, v80, v178
	v_add_f32_e32 v178, v81, v178
	v_add_f32_e32 v178, v82, v178
	v_mfma_f32_32x32x16_bf16 v[114:129], v[198:201], v[150:153], v[114:129]
	v_add_f32_e32 v178, v83, v178
	v_add_f32_e32 v178, v84, v178
	v_add_f32_e32 v178, v85, v178
	v_add_f32_e32 v178, v86, v178
	v_add_f32_e32 v178, v87, v178
	v_add_f32_e32 v178, v88, v178
	v_add_f32_e32 v178, v89, v178
	s_waitcnt lgkmcnt(4)
	v_mfma_f32_32x32x16_bf16 v[98:113], v[238:241], v[158:161], v[98:113]
	v_add_f32_e32 v178, v90, v178
	v_add_f32_e32 v178, v91, v178
	v_add_f32_e32 v178, v92, v178
	v_add_f32_e32 v178, v93, v178
	v_add_f32_e32 v178, v94, v178
	v_add_f32_e32 v178, v95, v178
	v_add_f32_e32 v178, v96, v178
	v_mfma_f32_32x32x16_bf16 v[114:129], v[206:209], v[158:161], v[114:129]
	v_add_f32_e32 v233, v97, v178
	v_mov_b32_e32 v235, v233
	s_nop 1
	v_permlane32_swap_b32_e32 v233, v235
	v_cvt_pk_bf16_f32 v198, v74, v75
	v_cvt_pk_bf16_f32 v199, v76, v77
	v_cvt_pk_bf16_f32 v200, v78, v79
	s_waitcnt lgkmcnt(2)
	v_mfma_f32_32x32x16_bf16 v[98:113], v[246:249], v[146:149], v[98:113]
	v_cvt_pk_bf16_f32 v201, v80, v81
	ds_read_b64_tr_b16 v[66:67], v217 offset:0
	ds_read_b64_tr_b16 v[68:69], v217 offset:0x800
	ds_read_b64_tr_b16 v[70:71], v217 offset:0x1000
	ds_read_b64_tr_b16 v[72:73], v217 offset:0x1800
	ds_read_b64_tr_b16 v[74:75], v217 offset:0x2000
	ds_read_b64_tr_b16 v[76:77], v217 offset:0x2800
	ds_read_b64_tr_b16 v[78:79], v217 offset:0x3000
	ds_read_b64_tr_b16 v[80:81], v217 offset:0x3800
	v_cvt_pk_bf16_f32 v206, v82, v83
	v_cvt_pk_bf16_f32 v207, v84, v85
	v_cvt_pk_bf16_f32 v208, v86, v87
	v_cvt_pk_bf16_f32 v209, v88, v89
	v_cvt_pk_bf16_f32 v202, v90, v91
	v_cvt_pk_bf16_f32 v203, v92, v93
	v_mfma_f32_32x32x16_bf16 v[114:129], v[242:245], v[146:149], v[114:129]
	v_cvt_pk_bf16_f32 v204, v94, v95
	v_cvt_pk_bf16_f32 v205, v96, v97
	v_permlane32_swap_b32_e32 v195, v197
	v_permlane32_swap_b32_e32 v198, v200
	v_permlane32_swap_b32_e32 v199, v201
	s_waitcnt lgkmcnt(8)
	v_mfma_f32_32x32x16_bf16 v[98:113], v[250:253], v[154:157], v[98:113]
	v_permlane32_swap_b32_e32 v206, v208
	v_permlane32_swap_b32_e32 v207, v209
	v_permlane32_swap_b32_e32 v202, v204
	v_permlane32_swap_b32_e32 v203, v205
	v_mfma_f32_32x32x16_bf16 v[114:129], v[182:185], v[154:157], v[114:129]
	v_add_co_u32_e32 v238, vcc, s67, v212
	s_nop 1
	v_addc_co_u32_e32 v239, vcc, -1, v213, vcc
	v_add_co_u32_e32 v240, vcc, s80, v212
	s_nop 1
	v_addc_co_u32_e32 v241, vcc, -1, v213, vcc
	global_load_dwordx4 v[178:181], v[238:239], off
	global_load_dwordx4 v[182:185], v[238:239], off offset:-512
	global_load_dwordx4 v[190:193], v[240:241], off
	global_load_dwordx4 v[186:189], v[240:241], off offset:-512
	s_waitcnt lgkmcnt(0)
	s_nop 0
	v_mfma_f32_32x32x16_bf16 v[50:65], v[194:197], v[66:69], v[50:65]
	v_max_f32_e32 v66, v114, v115
	v_max3_f32 v66, v66, v116, v117
	v_max3_f32 v66, v66, v118, v119
	v_max3_f32 v66, v66, v120, v121
	v_max3_f32 v66, v66, v122, v123
	v_mfma_f32_32x32x16_bf16 v[50:65], v[198:201], v[70:73], v[50:65]
	v_max3_f32 v66, v66, v124, v125
	v_max3_f32 v68, v66, v126, v127
	ds_read_b64_tr_b16 v[66:67], v217 offset:0x200
	v_max3_f32 v86, v68, v128, v129
	ds_read_b64_tr_b16 v[68:69], v217 offset:0xa00
	ds_read_b64_tr_b16 v[70:71], v217 offset:0x1200
	ds_read_b64_tr_b16 v[72:73], v217 offset:0x1a00
	v_mfma_f32_32x32x16_bf16 v[50:65], v[206:209], v[74:77], v[50:65]
	ds_read_b64_tr_b16 v[74:75], v217 offset:0x2200
	ds_read_b64_tr_b16 v[76:77], v217 offset:0x2a00
	ds_read_b64_tr_b16 v[82:83], v217 offset:0x3200
	ds_read_b64_tr_b16 v[84:85], v217 offset:0x3a00
	s_waitcnt lgkmcnt(0)
; __device__ __forceinline__ void psm_decide(float pmax, const f32x16& p1, float& m_reg, float& mn, float& alpha) {
;   constexpr float C = SCALE * 1.4426950408889634f;
;   for (int r = 0; r < 16; ++r) pmax = fmaxf(pmax, p1[r]);
;   { auto rr = __builtin_amdgcn_permlane32_swap(__float_as_uint(pmax), __float_as_uint(pmax), false, false);
;     pmax = fmaxf(__uint_as_float(rr[0]), __uint_as_float(rr[1])); }
;   if (__builtin_expect(__all(pmax - m_reg <= THR / SCALE), 1)) { mn = m_reg; alpha = 1.f; }
;   else { mn = fmaxf(m_reg, pmax); alpha = __builtin_amdgcn_exp2f((m_reg - mn) * C); m_reg = mn; }
; }
; __device__ __forceinline__ void psm_scale(f32x16& p0, f32x16& p1, float mn) {
;   constexpr float C = SCALE * 1.4426950408889634f; const float mnC = -mn * C;
;   for (int r = 0; r < 16; ++r) p0[r] = fmaf(p0[r], C, mnC); for (int r = 0; r < 16; ++r) p1[r] = fmaf(p1[r], C, mnC);
; }
; __device__ __forceinline__ void finishSM(f32x16& p0, f32x16& p1, float alpha, float& l_reg, bf16x8& pa0, bf16x8& pa1, bf16x8& pa2, bf16x8& pa3) {
;   for (int r = 0; r < 16; ++r) p1[r] = __builtin_amdgcn_exp2f(p1[r]);
;   float ps = 0; for (int r = 0; r < 16; ++r) ps += p0[r]; for (int r = 0; r < 16; ++r) ps += p1[r];
;   { auto rr = __builtin_amdgcn_permlane32_swap(__float_as_uint(ps), __float_as_uint(ps), false, false);
;     ps = __uint_as_float(rr[0]) + __uint_as_float(rr[1]); }
;   l_reg = l_reg * alpha + ps;
;     ...
;   PK4(p0, 0, pa0); PK4(p0, 8, pa1); PK4(p1, 0, pa2); PK4(p1, 8, pa3);
;     ...
; }
; __device__ __forceinline__ void qkt(f32x16& p0, f32x16& p1, const bf16* Ks, const bf16x8* qr, int r32, int hi) {
;   p0 = f32x16{}; p1 = f32x16{};
;   for (int d0 = 0; d0 < 8; ++d0) { int cb = (d0 * 16 + hi * 8) * 2;
;     bf16x8 b0 = *reinterpret_cast<const bf16x8*>((const char*)Ks + KSWZ(r32, cb));
;     bf16x8 b1 = *reinterpret_cast<const bf16x8*>((const char*)Ks + KSWZ(32 + r32, cb));
;     p0 = __builtin_amdgcn_mfma_f32_32x32x16_bf16(b0, qr[d0], p0, 0, 0, 0);
;     p1 = __builtin_amdgcn_mfma_f32_32x32x16_bf16(b1, qr[d0], p1, 0, 0, 0); }
; }
; __device__ __forceinline__ int v_st(int k, int c) { const int kk = (k & ~0xC) | ((k & 4) << 1) | ((k & 8) >> 1); return ((kk >> 3) * 4 + (c >> 5)) * 512 + ((kk & 7) * 32 + (c & 31)) * 2; }
; __device__ __forceinline__ int v_rd_base(int lane) { return ((lane & 3) << 3) | (((lane >> 2) & 3) << 6) | (((lane >> 4) & 1) << 5) | (((lane >> 5) & 1) << 8); }
	v_mfma_f32_32x32x16_bf16 v[50:65], v[202:205], v[78:81], v[50:65]
	v_mfma_f32_32x32x16_bf16 v[34:49], v[194:197], v[66:69], v[34:49]
	v_max3_f32 v78, v86, v98, v99
	v_max3_f32 v78, v78, v100, v101
	v_max3_f32 v78, v78, v102, v103
	v_max3_f32 v78, v78, v104, v105
	v_max3_f32 v78, v78, v106, v107
	v_max3_f32 v78, v78, v108, v109
	v_max3_f32 v66, v78, v110, v111
	v_max3_f32 v66, v66, v112, v113
	v_mfma_f32_32x32x16_bf16 v[34:49], v[198:201], v[70:73], v[34:49]
	v_mov_b32_e32 v67, v66
	s_nop 1
	v_permlane32_swap_b32_e32 v66, v67
	v_max_f32_e32 v66, v66, v67
	v_sub_f32_e32 v67, v66, v237
	v_cmp_ge_f32_e32 vcc, s62, v67
	v_max_f32_e32 v66, v237, v66
	v_sub_f32_e32 v67, v237, v66
	v_mfma_f32_32x32x16_bf16 v[34:49], v[206:209], v[74:77], v[34:49]
	v_mul_f32_e32 v67, 0x3e0293ee, v67
	v_exp_f32_e32 v67, v67
	s_cmp_eq_u64 vcc, exec
	s_cselect_b64 vcc, -1, 0
	v_cndmask_b32_e32 v236, v66, v237, vcc
	v_cndmask_b32_e64 v238, v67, 1.0, vcc
	ds_read_b64_tr_b16 v[66:67], v217 offset:0x400
	ds_read_b64_tr_b16 v[68:69], v217 offset:0xc00
	v_mfma_f32_32x32x16_bf16 v[34:49], v[202:205], v[82:85], v[34:49]
	ds_read_b64_tr_b16 v[82:83], v217 offset:0x1400
	ds_read_b64_tr_b16 v[84:85], v217 offset:0x1c00
	ds_read_b64_tr_b16 v[240:241], v217 offset:0x2400
	ds_read_b64_tr_b16 v[242:243], v217 offset:0x2c00
	ds_read_b64_tr_b16 v[244:245], v217 offset:0x3400
	ds_read_b64_tr_b16 v[246:247], v217 offset:0x3c00
	s_waitcnt lgkmcnt(0)
	v_mfma_f32_32x32x16_bf16 v[18:33], v[194:197], v[66:69], v[18:33]
	v_mul_f32_e32 v248, 0xbe0293ee, v236
	v_fma_f32 v80, v128, s12, v248
	v_fma_f32 v81, v129, s12, v248
	v_fma_f32 v78, v126, s12, v248
	v_fma_f32 v79, v127, s12, v248
	v_pk_fma_f32 v[76:77], v[124:125], s[12:13], v[248:249] op_sel_hi:[1,0,0]
	v_pk_fma_f32 v[74:75], v[122:123], s[12:13], v[248:249] op_sel_hi:[1,0,0]
	v_pk_fma_f32 v[72:73], v[120:121], s[12:13], v[248:249] op_sel_hi:[1,0,0]
	v_pk_fma_f32 v[70:71], v[118:119], s[12:13], v[248:249] op_sel_hi:[1,0,0]
	v_mfma_f32_32x32x16_bf16 v[18:33], v[198:201], v[82:85], v[18:33]
	v_fma_f32 v68, v116, s12, v248
	v_fma_f32 v69, v117, s12, v248
	v_fma_f32 v66, v114, s12, v248
	v_fma_f32 v67, v115, s12, v248
	v_fma_f32 v96, v112, s12, v248
	v_fma_f32 v97, v113, s12, v248
	v_pk_fma_f32 v[94:95], v[110:111], s[12:13], v[248:249] op_sel_hi:[1,0,0]
	v_pk_fma_f32 v[92:93], v[108:109], s[12:13], v[248:249] op_sel_hi:[1,0,0]
	v_pk_fma_f32 v[90:91], v[106:107], s[12:13], v[248:249] op_sel_hi:[1,0,0]
	v_pk_fma_f32 v[88:89], v[104:105], s[12:13], v[248:249] op_sel_hi:[1,0,0]
	v_mfma_f32_32x32x16_bf16 v[18:33], v[206:209], v[240:243], v[18:33]
	v_fma_f32 v86, v102, s12, v248
	v_fma_f32 v87, v103, s12, v248
	v_fma_f32 v84, v100, s12, v248
	v_fma_f32 v85, v101, s12, v248
	v_fma_f32 v82, v98, s12, v248
	v_fma_f32 v83, v99, s12, v248
	ds_read_b64_tr_b16 v[98:99], v217 offset:0x600
	ds_read_b64_tr_b16 v[100:101], v217 offset:0xe00
	ds_read_b64_tr_b16 v[102:103], v217 offset:0x1600
	ds_read_b64_tr_b16 v[104:105], v217 offset:0x1e00
	v_mfma_f32_32x32x16_bf16 v[18:33], v[202:205], v[244:247], v[18:33]
	ds_read_b64_tr_b16 v[108:109], v217 offset:0x2600
	ds_read_b64_tr_b16 v[110:111], v217 offset:0x2e00
	ds_read_b64_tr_b16 v[114:115], v217 offset:0x3600
	ds_read_b64_tr_b16 v[116:117], v217 offset:0x3e00
	s_waitcnt lgkmcnt(0)
	v_mfma_f32_32x32x16_bf16 v[2:17], v[194:197], v[98:101], v[2:17]
	v_exp_f32_e32 v98, v66
	v_exp_f32_e32 v99, v67
	v_exp_f32_e32 v100, v68
	v_exp_f32_e32 v101, v69
	v_exp_f32_e32 v106, v74
	v_exp_f32_e32 v107, v75
	v_exp_f32_e32 v112, v80
	v_mfma_f32_32x32x16_bf16 v[2:17], v[198:201], v[102:105], v[2:17]
	v_exp_f32_e32 v102, v70
	v_exp_f32_e32 v103, v71
	v_exp_f32_e32 v104, v72
	v_exp_f32_e32 v105, v73
	v_exp_f32_e32 v113, v81
	v_mfma_f32_32x32x16_bf16 v[2:17], v[206:209], v[108:111], v[2:17]
	v_exp_f32_e32 v108, v76
	v_exp_f32_e32 v109, v77
	v_exp_f32_e32 v110, v78
	v_exp_f32_e32 v111, v79
	v_mfma_f32_32x32x16_bf16 v[2:17], v[202:205], v[114:117], v[2:17]
	s_waitcnt vmcnt(4)
	v_cmp_gt_f32_e32 vcc, 1.0, v238
	ds_write_b128 v219, v[174:177] offset:32768
	ds_write_b128 v220, v[162:165] offset:32768
	s_cbranch_vccz .LBB0_175
	s_and_saveexec_b64 s[16:17], s[2:3]
	ds_write_b32 v214, v238 offset:128
	s_or_b64 exec, exec, s[16:17]
	s_waitcnt lgkmcnt(0)
	v_add_u32_e32 v78, s95, v210
	ds_read_b128 v[66:69], v78 offset:224
	ds_read_b128 v[70:73], v78 offset:192
	ds_read_b128 v[74:77], v78 offset:160
	ds_read_b128 v[78:81], v78 offset:128
	s_waitcnt lgkmcnt(3)
	v_pk_mul_f32 v[62:63], v[62:63], v[66:67]
	s_waitcnt lgkmcnt(2)
	v_pk_mul_f32 v[58:59], v[58:59], v[70:71]
	s_waitcnt lgkmcnt(1)
	v_pk_mul_f32 v[54:55], v[54:55], v[74:75]
	v_pk_mul_f32 v[64:65], v[64:65], v[68:69]
	v_pk_mul_f32 v[60:61], v[60:61], v[72:73]
	v_pk_mul_f32 v[56:57], v[56:57], v[76:77]
	s_waitcnt lgkmcnt(0)
	v_pk_mul_f32 v[52:53], v[52:53], v[80:81]
	v_pk_mul_f32 v[50:51], v[50:51], v[78:79]
	v_pk_mul_f32 v[46:47], v[46:47], v[66:67]
	v_pk_mul_f32 v[42:43], v[42:43], v[70:71]
	v_pk_mul_f32 v[38:39], v[38:39], v[74:75]
	v_pk_mul_f32 v[48:49], v[48:49], v[68:69]
	v_pk_mul_f32 v[44:45], v[44:45], v[72:73]
	v_pk_mul_f32 v[40:41], v[40:41], v[76:77]
	v_pk_mul_f32 v[36:37], v[36:37], v[80:81]
	v_pk_mul_f32 v[34:35], v[34:35], v[78:79]
	v_pk_mul_f32 v[30:31], v[30:31], v[66:67]
	v_pk_mul_f32 v[26:27], v[26:27], v[70:71]
	v_pk_mul_f32 v[22:23], v[22:23], v[74:75]
	v_pk_mul_f32 v[32:33], v[32:33], v[68:69]
	v_pk_mul_f32 v[28:29], v[28:29], v[72:73]
	v_pk_mul_f32 v[24:25], v[24:25], v[76:77]
	v_pk_mul_f32 v[20:21], v[20:21], v[80:81]
	v_pk_mul_f32 v[18:19], v[18:19], v[78:79]
	v_pk_mul_f32 v[14:15], v[14:15], v[66:67]
	v_pk_mul_f32 v[10:11], v[10:11], v[70:71]
	v_pk_mul_f32 v[6:7], v[6:7], v[74:75]
	v_pk_mul_f32 v[16:17], v[16:17], v[68:69]
	v_pk_mul_f32 v[12:13], v[12:13], v[72:73]
	v_pk_mul_f32 v[8:9], v[8:9], v[76:77]
	v_pk_mul_f32 v[4:5], v[4:5], v[80:81]
	v_pk_mul_f32 v[2:3], v[2:3], v[78:79]
; #define SBAR() __builtin_amdgcn_sched_barrier(0)
; #define SLOAD(i, k0) do { const long to_ = (long)(k0) * ldk * 2; const char* vt_ = (const char*)Vh + to_; const char* kt_ = (const char*)Kh + to_; \
;     sr_[i].vs0 = *(const bf16x8*)(vt_ + toff); sr_[i].vs1 = *(const bf16x8*)(vt_ + h32 + toff); \
;     sr_[i].ks0 = *(const bf16x8*)(kt_ + toff); sr_[i].ks1 = *(const bf16x8*)(kt_ + h32 + toff); } while (0)
; __device__ __forceinline__ void finishSM(f32x16& p0, f32x16& p1, float alpha, float& l_reg, bf16x8& pa0, bf16x8& pa1, bf16x8& pa2, bf16x8& pa3) {
;   for (int r = 0; r < 16; ++r) p1[r] = __builtin_amdgcn_exp2f(p1[r]);
;   float ps = 0; for (int r = 0; r < 16; ++r) ps += p0[r]; for (int r = 0; r < 16; ++r) ps += p1[r];
;   { auto rr = __builtin_amdgcn_permlane32_swap(__float_as_uint(ps), __float_as_uint(ps), false, false);
;     ps = __uint_as_float(rr[0]) + __uint_as_float(rr[1]); }
;   l_reg = l_reg * alpha + ps;
;     ...
;   PK4(p0, 0, pa0); PK4(p0, 8, pa1); PK4(p1, 0, pa2); PK4(p1, 8, pa3);
;     ...
; }
; __device__ __forceinline__ void qkt(f32x16& p0, f32x16& p1, const bf16* Ks, const bf16x8* qr, int r32, int hi) {
;   p0 = f32x16{}; p1 = f32x16{};
;   for (int d0 = 0; d0 < 8; ++d0) { int cb = (d0 * 16 + hi * 8) * 2;
;     bf16x8 b0 = *reinterpret_cast<const bf16x8*>((const char*)Ks + KSWZ(r32, cb));
;     bf16x8 b1 = *reinterpret_cast<const bf16x8*>((const char*)Ks + KSWZ(32 + r32, cb));
;     p0 = __builtin_amdgcn_mfma_f32_32x32x16_bf16(b0, qr[d0], p0, 0, 0, 0);
;     p1 = __builtin_amdgcn_mfma_f32_32x32x16_bf16(b1, qr[d0], p1, 0, 0, 0); }
; }
; template <int MODE, int QMODE> ...
;     ...
;     SBAR(); qkt(pA0, pA1, K_lds, qr, r32, hi);
;     finishSM(pB0, pB1, alB, l_reg, pa0, pa1, pa2, pa3); SBAR();
;     if (SDEPTH == 1 || j + 3 < NT) SLOAD(SE, (j + 1 + SDEPTH) * KVBLK); SBAR();
;     PVSM(vb0 + (int)SHM_V, pA0, pA1, (j + 1) * KVBLK, mnA, alA);
.LBB0_175:
	s_waitcnt lgkmcnt(0)
	s_barrier
	ds_write_b128 v221, v[166:169]
	ds_write_b128 v222, v[170:173]
	ds_read_b128 v[66:69], v218 offset:32768
	ds_read_b128 v[70:73], v218 offset:40960
	ds_read_b128 v[194:197], v223 offset:32768
	ds_read_b128 v[198:201], v223 offset:40960
	ds_read_b128 v[162:165], v227 offset:32768
	ds_read_b128 v[166:169], v227 offset:40960
	ds_read_b128 v[170:173], v228 offset:32768
	ds_read_b128 v[174:177], v228 offset:40960
	v_exp_f32_e32 v82, v82
	v_exp_f32_e32 v83, v83
	s_waitcnt lgkmcnt(7)
	v_mfma_f32_32x32x16_bf16 v[114:129], v[66:69], v[134:137], 0
	v_exp_f32_e32 v84, v84
	v_exp_f32_e32 v85, v85
	v_exp_f32_e32 v86, v86
	v_exp_f32_e32 v87, v87
	v_exp_f32_e32 v88, v88
	v_exp_f32_e32 v89, v89
	v_exp_f32_e32 v90, v90
	s_waitcnt lgkmcnt(6)
	v_mfma_f32_32x32x16_bf16 v[66:81], v[70:73], v[134:137], 0
	v_exp_f32_e32 v91, v91
	v_exp_f32_e32 v92, v92
	v_exp_f32_e32 v93, v93
	v_exp_f32_e32 v94, v94
	v_exp_f32_e32 v95, v95
	v_exp_f32_e32 v96, v96
	v_exp_f32_e32 v97, v97
	ds_read_b128 v[242:245], v229 offset:32768
	ds_read_b128 v[246:249], v229 offset:40960
	ds_read_b128 v[250:253], v231 offset:32768
	s_waitcnt lgkmcnt(8)
	v_mfma_f32_32x32x16_bf16 v[114:129], v[194:197], v[142:145], v[114:129]
	v_add_f32_e32 v241, 0, v98
	v_add_f32_e32 v241, v99, v241
	v_add_f32_e32 v241, v100, v241
	v_add_f32_e32 v241, v101, v241
	v_add_f32_e32 v241, v102, v241
	v_add_f32_e32 v241, v103, v241
	s_waitcnt lgkmcnt(7)
	v_mfma_f32_32x32x16_bf16 v[66:81], v[198:201], v[142:145], v[66:81]
	v_add_f32_e32 v241, v104, v241
	v_add_f32_e32 v241, v105, v241
	v_add_f32_e32 v241, v106, v241
	v_add_f32_e32 v241, v107, v241
	v_add_f32_e32 v241, v108, v241
	v_add_f32_e32 v241, v109, v241
	s_waitcnt lgkmcnt(6)
	v_mfma_f32_32x32x16_bf16 v[114:129], v[162:165], v[130:133], v[114:129]
	v_add_f32_e32 v241, v110, v241
	v_add_f32_e32 v241, v111, v241
	v_add_f32_e32 v241, v112, v241
	v_add_f32_e32 v241, v113, v241
	v_cvt_pk_bf16_f32 v206, v98, v99
	v_cvt_pk_bf16_f32 v207, v100, v101
	s_waitcnt lgkmcnt(5)
	v_mfma_f32_32x32x16_bf16 v[66:81], v[166:169], v[130:133], v[66:81]
	ds_read_b128 v[162:165], v231 offset:40960
	ds_read_b128 v[166:169], v230 offset:32768
	v_cvt_pk_bf16_f32 v208, v102, v103
	v_cvt_pk_bf16_f32 v209, v104, v105
	v_add_f32_e32 v241, v82, v241
	v_add_f32_e32 v241, v83, v241
	v_add_f32_e32 v241, v84, v241
	s_waitcnt lgkmcnt(6)
	v_mfma_f32_32x32x16_bf16 v[114:129], v[170:173], v[138:141], v[114:129]
	v_permlane32_swap_b32_e32 v206, v208
	v_add_f32_e32 v241, v85, v241
	v_add_f32_e32 v241, v86, v241
	v_add_f32_e32 v241, v87, v241
	v_add_f32_e32 v241, v88, v241
	s_waitcnt lgkmcnt(5)
	v_mfma_f32_32x32x16_bf16 v[66:81], v[174:177], v[138:141], v[66:81]
	ds_read_b128 v[170:173], v230 offset:40960
	ds_read_b128 v[174:177], v232 offset:32768
	v_permlane32_swap_b32_e32 v207, v209
	v_add_f32_e32 v241, v89, v241
	v_add_f32_e32 v241, v90, v241
	v_add_f32_e32 v241, v91, v241
	v_add_f32_e32 v241, v92, v241
	s_waitcnt lgkmcnt(6)
	v_mfma_f32_32x32x16_bf16 v[114:129], v[242:245], v[150:153], v[114:129]
	v_cvt_pk_bf16_f32 v198, v106, v107
	v_cvt_pk_bf16_f32 v199, v108, v109
	v_cvt_pk_bf16_f32 v200, v110, v111
	v_cvt_pk_bf16_f32 v201, v112, v113
	v_add_f32_e32 v241, v93, v241
	v_add_f32_e32 v241, v94, v241
	s_waitcnt lgkmcnt(5)
	v_mfma_f32_32x32x16_bf16 v[66:81], v[246:249], v[150:153], v[66:81]
	ds_read_b128 v[242:245], v232 offset:40960
	v_permlane32_swap_b32_e32 v198, v200
	v_permlane32_swap_b32_e32 v199, v201
	v_add_f32_e32 v241, v95, v241
	v_add_f32_e32 v241, v96, v241
	s_waitcnt lgkmcnt(5)
	v_mfma_f32_32x32x16_bf16 v[114:129], v[250:253], v[158:161], v[114:129]
	v_add_f32_e32 v239, v97, v241
	v_mov_b32_e32 v240, v239
	v_cvt_pk_bf16_f32 v202, v82, v83
	v_cvt_pk_bf16_f32 v203, v84, v85
	v_cvt_pk_bf16_f32 v204, v86, v87
	v_cvt_pk_bf16_f32 v205, v88, v89
	s_waitcnt lgkmcnt(4)
	v_mfma_f32_32x32x16_bf16 v[66:81], v[162:165], v[158:161], v[66:81]
	v_permlane32_swap_b32_e32 v239, v240
	v_permlane32_swap_b32_e32 v202, v204
	v_permlane32_swap_b32_e32 v203, v205
	s_waitcnt lgkmcnt(3)
	v_mfma_f32_32x32x16_bf16 v[114:129], v[166:169], v[146:149], v[114:129]
	v_cvt_pk_bf16_f32 v194, v90, v91
	v_cvt_pk_bf16_f32 v195, v92, v93
	v_cvt_pk_bf16_f32 v196, v94, v95
	v_cvt_pk_bf16_f32 v197, v96, v97
	s_waitcnt lgkmcnt(2)
	v_mfma_f32_32x32x16_bf16 v[66:81], v[170:173], v[146:149], v[66:81]
	v_permlane32_swap_b32_e32 v194, v196
	v_permlane32_swap_b32_e32 v195, v197
	ds_read_b64_tr_b16 v[82:83], v216 offset:0
	ds_read_b64_tr_b16 v[84:85], v216 offset:0x800
	ds_read_b64_tr_b16 v[86:87], v216 offset:0x1000
	ds_read_b64_tr_b16 v[88:89], v216 offset:0x1800
	ds_read_b64_tr_b16 v[90:91], v216 offset:0x2000
	ds_read_b64_tr_b16 v[92:93], v216 offset:0x2800
	ds_read_b64_tr_b16 v[94:95], v216 offset:0x3000
	ds_read_b64_tr_b16 v[96:97], v216 offset:0x3800
	s_waitcnt lgkmcnt(9)
	v_mfma_f32_32x32x16_bf16 v[114:129], v[174:177], v[154:157], v[114:129]
	s_waitcnt lgkmcnt(8)
	v_mfma_f32_32x32x16_bf16 v[66:81], v[242:245], v[154:157], v[66:81]
	s_add_i32 s96, s96, 2
	s_cmp_ge_u32 s96, s94
	s_cselect_b64 s[16:17], -1, 0
	s_and_b64 vcc, exec, s[16:17]
	s_cbranch_vccnz .LBB0_177
	v_add_co_u32_e32 v250, vcc, 0xfffd0000, v212
	s_nop 1
	v_addc_co_u32_e32 v251, vcc, -1, v213, vcc
	global_load_dwordx4 v[166:169], v[250:251], off
	global_load_dwordx4 v[174:177], v[250:251], off offset:-512
	global_load_dwordx4 v[170:173], v[212:213], off
	global_load_dwordx4 v[162:165], v[212:213], off offset:-512
; #define SBAR() __builtin_amdgcn_sched_barrier(0)
; __device__ __forceinline__ void psm_decide(float pmax, const f32x16& p1, float& m_reg, float& mn, float& alpha) {
;   constexpr float C = SCALE * 1.4426950408889634f;
;   for (int r = 0; r < 16; ++r) pmax = fmaxf(pmax, p1[r]);
;   { auto rr = __builtin_amdgcn_permlane32_swap(__float_as_uint(pmax), __float_as_uint(pmax), false, false);
;     pmax = fmaxf(__uint_as_float(rr[0]), __uint_as_float(rr[1])); }
;   if (__builtin_expect(__all(pmax - m_reg <= THR / SCALE), 1)) { mn = m_reg; alpha = 1.f; }
;   else { mn = fmaxf(m_reg, pmax); alpha = __builtin_amdgcn_exp2f((m_reg - mn) * C); m_reg = mn; }
; }
; __device__ __forceinline__ void psm_scale(f32x16& p0, f32x16& p1, float mn) {
;   constexpr float C = SCALE * 1.4426950408889634f; const float mnC = -mn * C;
;   for (int r = 0; r < 16; ++r) p0[r] = fmaf(p0[r], C, mnC); for (int r = 0; r < 16; ++r) p1[r] = fmaf(p1[r], C, mnC);
; }
; template <int D0> __device__ __forceinline__ void pv_one(f32x16& od, int vb, bf16x8 pa0, bf16x8 pa1, bf16x8 pa2, bf16x8 pa3) {
;   const s16x4 l0 = tr_read<v_rd_off(D0, 0, 0)>(vb), h0 = tr_read<v_rd_off(D0, 0, 1)>(vb), l1 = tr_read<v_rd_off(D0, 1, 0)>(vb), h1 = tr_read<v_rd_off(D0, 1, 1)>(vb);
;   const s16x4 l2 = tr_read<v_rd_off(D0, 2, 0)>(vb), h2 = tr_read<v_rd_off(D0, 2, 1)>(vb), l3 = tr_read<v_rd_off(D0, 3, 0)>(vb), h3 = tr_read<v_rd_off(D0, 3, 1)>(vb);
;   asm volatile("s_waitcnt lgkmcnt(0)" ::: "memory"); SBAR();
;     ...
;   od = __builtin_amdgcn_mfma_f32_32x32x16_bf16(pa0, PK(l0, h0), od, 0, 0, 0);
;   od = __builtin_amdgcn_mfma_f32_32x32x16_bf16(pa1, PK(l1, h1), od, 0, 0, 0);
;   od = __builtin_amdgcn_mfma_f32_32x32x16_bf16(pa2, PK(l2, h2), od, 0, 0, 0);
;   od = __builtin_amdgcn_mfma_f32_32x32x16_bf16(pa3, PK(l3, h3), od, 0, 0, 0);
;     ...
; }
.LBB0_177:
	s_waitcnt lgkmcnt(0)
	s_nop 0
	v_mfma_f32_32x32x16_bf16 v[50:65], v[206:209], v[82:85], v[50:65]
	v_max_f32_e32 v82, v114, v115
	v_max3_f32 v82, v82, v116, v117
	v_max3_f32 v82, v82, v118, v119
	v_max3_f32 v82, v82, v120, v121
	v_max3_f32 v82, v82, v122, v123
	v_mfma_f32_32x32x16_bf16 v[50:65], v[198:201], v[86:89], v[50:65]
	v_max3_f32 v82, v82, v124, v125
	v_max3_f32 v84, v82, v126, v127
	ds_read_b64_tr_b16 v[82:83], v216 offset:0x200
	v_max3_f32 v102, v84, v128, v129
	ds_read_b64_tr_b16 v[84:85], v216 offset:0xa00
	ds_read_b64_tr_b16 v[86:87], v216 offset:0x1200
	ds_read_b64_tr_b16 v[88:89], v216 offset:0x1a00
	v_mfma_f32_32x32x16_bf16 v[50:65], v[202:205], v[90:93], v[50:65]
	ds_read_b64_tr_b16 v[90:91], v216 offset:0x2200
	ds_read_b64_tr_b16 v[92:93], v216 offset:0x2a00
	ds_read_b64_tr_b16 v[98:99], v216 offset:0x3200
	ds_read_b64_tr_b16 v[100:101], v216 offset:0x3a00
	s_waitcnt lgkmcnt(0)
	v_mfma_f32_32x32x16_bf16 v[50:65], v[194:197], v[94:97], v[50:65]
	v_max3_f32 v94, v102, v66, v67
	v_mfma_f32_32x32x16_bf16 v[34:49], v[206:209], v[82:85], v[34:49]
	v_max3_f32 v94, v94, v68, v69
	v_max3_f32 v94, v94, v70, v71
	v_max3_f32 v94, v94, v72, v73
	v_max3_f32 v94, v94, v74, v75
	v_max3_f32 v94, v94, v76, v77
	v_max3_f32 v82, v94, v78, v79
	v_max3_f32 v82, v82, v80, v81
	v_mov_b32_e32 v83, v82
	v_mfma_f32_32x32x16_bf16 v[34:49], v[198:201], v[86:89], v[34:49]
	s_nop 0
	v_permlane32_swap_b32_e32 v82, v83
	v_max_f32_e32 v82, v82, v83
	v_sub_f32_e32 v83, v82, v236
	v_cmp_ge_f32_e32 vcc, s62, v83
	v_max_f32_e32 v82, v236, v82
	v_sub_f32_e32 v83, v236, v82
	v_mul_f32_e32 v83, 0x3e0293ee, v83
	v_mfma_f32_32x32x16_bf16 v[34:49], v[202:205], v[90:93], v[34:49]
	v_exp_f32_e32 v83, v83
	s_cmp_eq_u64 vcc, exec
	s_cselect_b64 vcc, -1, 0
	v_cndmask_b32_e32 v237, v82, v236, vcc
	v_cndmask_b32_e64 v236, v83, 1.0, vcc
	ds_read_b64_tr_b16 v[82:83], v216 offset:0x400
	ds_read_b64_tr_b16 v[84:85], v216 offset:0xc00
	ds_read_b64_tr_b16 v[86:87], v216 offset:0x1400
	v_mfma_f32_32x32x16_bf16 v[34:49], v[194:197], v[98:101], v[34:49]
	ds_read_b64_tr_b16 v[88:89], v216 offset:0x1c00
	ds_read_b64_tr_b16 v[242:243], v216 offset:0x2400
	ds_read_b64_tr_b16 v[244:245], v216 offset:0x2c00
	ds_read_b64_tr_b16 v[246:247], v216 offset:0x3400
	ds_read_b64_tr_b16 v[248:249], v216 offset:0x3c00
	s_waitcnt lgkmcnt(0)
	v_mfma_f32_32x32x16_bf16 v[18:33], v[206:209], v[82:85], v[18:33]
	v_mul_f32_e32 v250, 0xbe0293ee, v237
	v_fma_f32 v112, v128, s12, v250
	v_fma_f32 v113, v129, s12, v250
	v_fma_f32 v110, v126, s12, v250
	v_fma_f32 v111, v127, s12, v250
	v_pk_fma_f32 v[108:109], v[124:125], s[12:13], v[250:251] op_sel_hi:[1,0,0]
	v_pk_fma_f32 v[106:107], v[122:123], s[12:13], v[250:251] op_sel_hi:[1,0,0]
	v_pk_fma_f32 v[104:105], v[120:121], s[12:13], v[250:251] op_sel_hi:[1,0,0]
	v_pk_fma_f32 v[102:103], v[118:119], s[12:13], v[250:251] op_sel_hi:[1,0,0]
	v_mfma_f32_32x32x16_bf16 v[18:33], v[198:201], v[86:89], v[18:33]
	v_fma_f32 v100, v116, s12, v250
	v_fma_f32 v101, v117, s12, v250
	v_fma_f32 v98, v114, s12, v250
	v_fma_f32 v99, v115, s12, v250
	v_fma_f32 v96, v80, s12, v250
	v_fma_f32 v97, v81, s12, v250
	v_pk_fma_f32 v[94:95], v[78:79], s[12:13], v[250:251] op_sel_hi:[1,0,0]
	v_pk_fma_f32 v[92:93], v[76:77], s[12:13], v[250:251] op_sel_hi:[1,0,0]
	v_pk_fma_f32 v[90:91], v[74:75], s[12:13], v[250:251] op_sel_hi:[1,0,0]
	v_pk_fma_f32 v[88:89], v[72:73], s[12:13], v[250:251] op_sel_hi:[1,0,0]
	v_mfma_f32_32x32x16_bf16 v[18:33], v[202:205], v[242:245], v[18:33]
	v_fma_f32 v86, v70, s12, v250
	v_fma_f32 v87, v71, s12, v250
	v_fma_f32 v84, v68, s12, v250
	v_fma_f32 v85, v69, s12, v250
	v_fma_f32 v82, v66, s12, v250
	v_fma_f32 v83, v67, s12, v250
	ds_read_b64_tr_b16 v[66:67], v216 offset:0x600
	ds_read_b64_tr_b16 v[68:69], v216 offset:0xe00
	ds_read_b64_tr_b16 v[70:71], v216 offset:0x1600
	ds_read_b64_tr_b16 v[72:73], v216 offset:0x1e00
	v_mfma_f32_32x32x16_bf16 v[18:33], v[194:197], v[246:249], v[18:33]
	ds_read_b64_tr_b16 v[76:77], v216 offset:0x2600
	ds_read_b64_tr_b16 v[78:79], v216 offset:0x2e00
	ds_read_b64_tr_b16 v[114:115], v216 offset:0x3600
	ds_read_b64_tr_b16 v[116:117], v216 offset:0x3e00
	s_waitcnt lgkmcnt(0)
	v_mfma_f32_32x32x16_bf16 v[2:17], v[206:209], v[66:69], v[2:17]
	v_exp_f32_e32 v66, v98
	v_exp_f32_e32 v67, v99
	v_exp_f32_e32 v68, v100
	v_exp_f32_e32 v69, v101
	v_exp_f32_e32 v74, v106
	v_exp_f32_e32 v75, v107
	v_exp_f32_e32 v80, v112
	v_mfma_f32_32x32x16_bf16 v[2:17], v[198:201], v[70:73], v[2:17]
	v_exp_f32_e32 v70, v102
	v_exp_f32_e32 v71, v103
	v_exp_f32_e32 v72, v104
	v_exp_f32_e32 v73, v105
	v_exp_f32_e32 v81, v113
	v_mfma_f32_32x32x16_bf16 v[2:17], v[202:205], v[76:79], v[2:17]
	v_exp_f32_e32 v76, v108
	v_exp_f32_e32 v77, v109
	v_exp_f32_e32 v78, v110
	v_exp_f32_e32 v79, v111
	v_mfma_f32_32x32x16_bf16 v[2:17], v[194:197], v[114:117], v[2:17]
	s_waitcnt vmcnt(4)
	s_cmp_ge_u32 s96, s94
	s_cbranch_scc0 .Lb_nodrain
	s_waitcnt vmcnt(0)
